# static s_setprio 1 for waves 0-3 (the half running a half-step ahead) over the prompt attention loop (7.4, other half)
# baseline (speedup 1.0000x reference)
; template <int VAR>
; __device__ __forceinline__ void attn_unit(const AUnit& u, LAS char* lds) {
;     ...
;     const int tid = tid_, wid = __builtin_amdgcn_readfirstlane(tid >> 6), lane = tid & 63, r32 = lane & 31, hi = lane >> 5;
;     const bool wact = wid < u.nwav;
;     const int jmax = u.jbase + (wid >> 1);
;     const bf16_t* gk0; const bf16_t* gk1; const bf16_t* gkr; const bf16_t* gv0; const bf16_t* gv1;
;     {
;         const int rk0 = (2 * wid) * 4 + (lane >> 4), rk1 = rk0 + 4, ph = lane & 15;
;         gk0 = u.Kn + (size_t)rk0 * 128 + ((ph ^ (rk0 & 15)) * 8);
;         gk1 = u.Kn + (size_t)rk1 * 128 + ((ph ^ (rk1 & 15)) * 8);
;         const int rr0 = wid * 8 + (lane >> 3), pr = lane & 7;
;         gkr = u.Kr + (size_t)rr0 * ROPE + ((pr ^ ((rr0 >> 1) & 7)) * 8);
; #pragma unroll
;         for (int i = 0; i < 2; ++i) {
;             const int st = (2 * wid + i) * 2 + (lane >> 5), o16 = lane & 31, kk = (st >> 2) * 8 + (o16 >> 2), c = (st & 3) * 32 + (o16 & 3) * 8;
;             const int key = (kk & ~0xC) | ((kk & 4) << 1) | ((kk & 8) >> 1);
;             const bf16_t* p = u.V + (size_t)key * 128 + c;
;             if (i == 0) gv0 = p; else gv1 = p;
;         }
;     }
;     ...
;     ADMA(0, 0);
;     bf16x8 qr[12];
;     {
;         const int wq = wact ? wid : 0;
;         const bf16_t* qp = u.Q + (size_t)(wq * 32 + r32) * QW + hi * 8;
; #pragma unroll
;         for (int d0 = 0; d0 < 12; ++d0) qr[d0] = *(const bf16x8*)(qp + d0 * 16);
.LBB0_941:
	s_lshl_b64 s[2:3], s[10:11], 8
	s_add_u32 s54, s2, s40
	s_addc_u32 s55, s3, s41
	s_mul_i32 s2, s55, 0x1800
	s_mul_hi_u32 s3, s54, 0x1800
	s_add_i32 s3, s3, s2
	s_mul_i32 s2, s54, 0x1800
	v_mov_b32_e32 v181, v0
	s_add_u32 s2, s76, s2
	s_addc_u32 s3, s77, s3
	v_readfirstlane_b32 s5, v181
	s_ashr_i32 s19, s5, 6
	s_lshl_b32 s56, s19, 3
	s_waitcnt lgkmcnt(0)
	v_bfe_u32 v2, v181, 4, 2
	s_waitcnt vmcnt(0)
	v_or_b32_e32 v4, s56, v2
	v_and_b32_e32 v2, 15, v181
	v_ashrrev_i32_e32 v5, 31, v4
	v_bitop3_b32 v10, v4, v2, 11 bitop3:0x6c
	v_bfe_u32 v2, v181, 3, 3
	v_or_b32_e32 v32, 4, v4
	v_lshlrev_b64 v[36:37], 8, v[4:5]
	v_bitop3_b32 v12, v4, v181, 4 bitop3:0x36
	v_or_b32_e32 v4, s56, v2
	v_ashrrev_i32_e32 v33, 31, v32
	v_ashrrev_i32_e32 v5, 31, v4
	v_bfe_u32 v2, v181, 2, 3
	v_lshlrev_b64 v[34:35], 8, v[32:33]
	v_lshlrev_b64 v[38:39], 7, v[4:5]
	v_lshrrev_b32_e32 v33, 1, v4
	v_bitop3_b32 v2, s56, -13, v2 bitop3:0xc8
	v_lshrrev_b32_e32 v4, 1, v181
	s_lshl_b32 s56, s19, 2
	v_and_b32_e32 v4, 8, v4
	s_and_b32 s56, s56, 4
	v_or3_b32 v4, v2, v4, s56
	s_lshl_b32 s56, s19, 11
	s_add_i32 s84, s56, 0
	s_lshl_b32 s56, s19, 10
	s_lshl_b32 s4, s10, 2
	s_add_i32 s87, s56, 0
	s_add_i32 s57, s4, 4
	s_ashr_i32 s91, s5, 7
	v_xor_b32_e32 v14, v33, v181
	s_add_i32 s85, s84, 0x8000
	s_add_i32 s86, s84, 0x8400
	s_add_i32 s88, s87, 0xc000
	s_add_i32 s89, s84, 0x400
	s_lshl_b32 s56, s19, 5
	v_lshl_add_u64 v[8:9], s[42:43], 0, v[36:37]
	v_lshlrev_b32_e32 v42, 4, v10
	v_mov_b32_e32 v43, v3
	v_lshlrev_b32_e32 v12, 4, v12
	v_and_b32_e32 v90, 32, v181
	v_lshrrev_b32_e32 v248, 6, v181
	v_lshl_add_u32 v248, v248, 10, v90
	v_add_u32_e32 v248, 0x15000, v248
	v_lshlrev_b32_e32 v89, 3, v181
	v_ashrrev_i32_e32 v5, 31, v4
	s_cmp_lt_i32 s19, 8
	v_lshl_add_u64 v[8:9], v[8:9], 0, v[42:43]
	v_lshl_add_u64 v[10:11], s[42:43], 0, v[34:35]
	v_and_b32_e32 v12, 0xf0, v12
	v_mov_b32_e32 v13, v3
	v_lshlrev_b32_e32 v14, 4, v14
	s_mov_b32 m0, s85
	v_and_or_b32 v6, v89, 24, v90
	v_lshlrev_b64 v[40:41], 8, v[4:5]
	s_cselect_b64 s[58:59], -1, 0
	v_lshl_add_u64 v[10:11], v[10:11], 0, v[12:13]
	v_lshl_add_u64 v[12:13], s[48:49], 0, v[38:39]
	v_and_b32_e32 v14, 0x70, v14
	v_mov_b32_e32 v15, v3
	global_load_lds_dwordx4 v[8:9], off
	s_mov_b32 m0, s86
	v_lshl_add_u64 v[4:5], s[46:47], 0, v[40:41]
	v_lshlrev_b32_e32 v2, 1, v6
	v_lshl_add_u64 v[12:13], v[12:13], 0, v[14:15]
	global_load_lds_dwordx4 v[10:11], off
	s_mov_b32 m0, s88
	s_and_b64 s[60:61], s[58:59], exec
	v_and_b32_e32 v180, 31, v181
	v_lshl_add_u64 v[4:5], v[4:5], 0, v[2:3]
	global_load_lds_dwordx4 v[12:13], off
	s_mov_b32 m0, s84
	s_cselect_b32 s60, s56, 0
	v_lshl_add_u64 v[6:7], v[4:5], 0, s[28:29]
	v_bfe_u32 v182, v181, 5, 1
	global_load_lds_dwordx4 v[4:5], off
	v_or_b32_e32 v43, s60, v180
	v_mov_b64_e32 v[4:5], s[2:3]
	s_mov_b32 m0, s89
	v_mad_i64_i32 v[4:5], s[2:3], v43, s45, v[4:5]
	v_lshlrev_b32_e32 v162, 4, v182
	v_mov_b32_e32 v163, v3
	global_load_lds_dwordx4 v[6:7], off
	v_lshl_add_u64 v[8:9], v[4:5], 0, v[162:163]
	global_load_dwordx4 v[28:31], v[8:9], off
	global_load_dwordx4 v[24:27], v[8:9], off offset:32
	global_load_dwordx4 v[20:23], v[8:9], off offset:64
	global_load_dwordx4 v[44:47], v[8:9], off offset:96
	global_load_dwordx4 v[48:51], v[8:9], off offset:128
	global_load_dwordx4 v[52:55], v[8:9], off offset:160
	global_load_dwordx4 v[108:111], v[8:9], off offset:192
	global_load_dwordx4 v[112:115], v[8:9], off offset:224
	global_load_dwordx4 v[12:15], v[8:9], off offset:256
	global_load_dwordx4 v[4:7], v[8:9], off offset:288
	global_load_dwordx4 v[16:19], v[8:9], off offset:320
	s_nop 0
	global_load_dwordx4 v[8:11], v[8:9], off offset:352
	s_lshl_b32 s2, s10, 13
	v_lshl_add_u32 v43, v43, 5, s2
	v_and_b32_e32 v88, 63, v181
	v_lshl_add_u32 v183, v180, 8, 0
	s_add_i32 s10, 0, 0x12000
	s_and_b32 s2, s5, 0x3fffffc0
	s_lshl_b32 s2, s2, 2
	s_add_i32 s90, s2, 0
	v_or_b32_e32 v36, v36, v42
	v_or_b32_e32 v40, v40, v2
	s_add_i32 s90, s90, 0x14000
	v_lshl_add_u64 v[172:173], s[50:51], 0, v[36:37]
	v_lshl_add_u64 v[178:179], s[50:51], 0, v[40:41]
	v_mov_b32_e32 v2, v3
	s_mov_b32 s19, 0
	s_add_i32 s91, s91, s4
	v_bitop3_b32 v212, v162, v89, s21 bitop3:0x78
	v_cmp_gt_u32_e64 s[2:3], 32, v88
	v_lshl_add_u32 v206, v180, 2, s90
	v_mov_b32_e32 v225, 0
	v_mov_b32_e32 v226, 0xf149f2ca
	s_waitcnt vmcnt(0)
; __device__ __forceinline__ u32x4 pack8(const float* f) { u32x4 w; w.x = cvtpk(f[0], f[1]); w.y = cvtpk(f[2], f[3]); w.z = cvtpk(f[4], f[5]); w.w = cvtpk(f[6], f[7]); return w; }
; __device__ __forceinline__ bf16x8 pack8(const f32x4& a, const f32x4& b) { u32x4 w; w.x = cpk(a.x, a.y); w.y = cpk(a.z, a.w); w.z = cpk(b.x, b.y); w.w = cpk(b.z, b.w); return __builtin_bit_cast(bf16x8, w); }
; template <int VAR>
; __device__ __forceinline__ void attn_unit(const AUnit& u, LAS char* lds) {
;     ...
;         float ssn = 0.f, ssr = 0.f;
; #pragma unroll
;         for (int d0 = 0; d0 < 12; ++d0) { float f[8]; unpack8(__builtin_bit_cast(u32x4, qr[d0]), f); float a = 0.f;
; #pragma unroll
;             for (int e = 0; e < 8; ++e) a += f[e] * f[e];
;             if (d0 < 8) ssn += a; else ssr += a; }
;         { auto rr = __builtin_amdgcn_permlane32_swap(__float_as_uint(ssn), __float_as_uint(ssn), false, false); ssn = __uint_as_float(rr[0]) + __uint_as_float(rr[1]); }
;         { auto rr = __builtin_amdgcn_permlane32_swap(__float_as_uint(ssr), __float_as_uint(ssr), false, false); ssr = __uint_as_float(rr[0]) + __uint_as_float(rr[1]); }
;         const float rn = rsqrtf(ssn * (1.f / 128) + NORM_EPS) * QSCALE, rr_ = rsqrtf(ssr * (1.f / ROPE) + NORM_EPS);
; #pragma unroll
;         for (int d0 = 0; d0 < 8; ++d0) { float f[8]; unpack8(__builtin_bit_cast(u32x4, qr[d0]), f);
;             const f32x4 g0 = *(const f32x4*)(u.gqn + d0 * 16 + hi * 8), g1 = *(const f32x4*)(u.gqn + d0 * 16 + hi * 8 + 4);
; #pragma unroll
;             for (int e = 0; e < 4; ++e) { f[e] *= rn * g0[e]; f[4 + e] *= rn * g1[e]; }
;             qr[d0] = __builtin_bit_cast(bf16x8, pack8(f)); }
	v_and_b32_e32 v104, 0xffff0000, v28
	v_and_b32_e32 v96, 0xffff0000, v24
	v_lshlrev_b32_e32 v106, 16, v28
	v_mul_f32_e32 v28, v104, v104
	v_lshlrev_b32_e32 v100, 16, v24
	v_mul_f32_e32 v24, v96, v96
	v_and_b32_e32 v79, 0xffff0000, v44
	v_and_b32_e32 v78, 0xffff0000, v20
	v_lshlrev_b32_e32 v101, 16, v29
	v_fmac_f32_e32 v28, v106, v106
	v_lshlrev_b32_e32 v94, 16, v25
	v_fmac_f32_e32 v24, v100, v100
	v_lshlrev_b32_e32 v83, 16, v44
	v_lshlrev_b32_e32 v82, 16, v20
	v_lshlrev_b32_e32 v76, 16, v21
	v_and_b32_e32 v74, 0xffff0000, v21
	v_pk_mul_f32 v[20:21], v[78:79], v[78:79]
	v_and_b32_e32 v97, 0xffff0000, v29
	v_fmac_f32_e32 v28, v101, v101
	v_and_b32_e32 v92, 0xffff0000, v25
	v_fmac_f32_e32 v24, v94, v94
	v_lshlrev_b32_e32 v77, 16, v45
	v_pk_fma_f32 v[20:21], v[82:83], v[82:83], v[20:21]
	v_lshlrev_b32_e32 v107, 16, v30
	v_fmac_f32_e32 v28, v97, v97
	v_lshlrev_b32_e32 v102, 16, v26
	v_fmac_f32_e32 v24, v92, v92
	v_and_b32_e32 v75, 0xffff0000, v45
	v_pk_fma_f32 v[20:21], v[76:77], v[76:77], v[20:21]
	v_and_b32_e32 v105, 0xffff0000, v30
	v_fmac_f32_e32 v28, v107, v107
	v_and_b32_e32 v98, 0xffff0000, v26
	v_fmac_f32_e32 v24, v102, v102
	v_lshlrev_b32_e32 v87, 16, v46
	v_lshlrev_b32_e32 v86, 16, v22
	v_pk_fma_f32 v[20:21], v[74:75], v[74:75], v[20:21]
	v_lshlrev_b32_e32 v103, 16, v31
	v_fmac_f32_e32 v28, v105, v105
	v_lshlrev_b32_e32 v95, 16, v27
	v_fmac_f32_e32 v24, v98, v98
	v_and_b32_e32 v85, 0xffff0000, v46
	v_and_b32_e32 v84, 0xffff0000, v22
	v_pk_fma_f32 v[20:21], v[86:87], v[86:87], v[20:21]
	v_and_b32_e32 v99, 0xffff0000, v31
	v_fmac_f32_e32 v28, v103, v103
	v_and_b32_e32 v93, 0xffff0000, v27
	v_fmac_f32_e32 v24, v95, v95
	v_lshlrev_b32_e32 v81, 16, v47
	v_lshlrev_b32_e32 v80, 16, v23
	v_pk_fma_f32 v[20:21], v[84:85], v[84:85], v[20:21]
	v_fmac_f32_e32 v28, v99, v99
	v_fmac_f32_e32 v24, v93, v93
	v_and_b32_e32 v73, 0xffff0000, v47
	v_and_b32_e32 v72, 0xffff0000, v23
	v_pk_fma_f32 v[20:21], v[80:81], v[80:81], v[20:21]
	v_add_f32_e32 v24, v28, v24
	v_pk_fma_f32 v[20:21], v[72:73], v[72:73], v[20:21]
	v_and_b32_e32 v65, 0xffff0000, v52
	v_add_f32_e32 v20, v24, v20
	v_and_b32_e32 v64, 0xffff0000, v48
	v_add_f32_e32 v22, v20, v21
	v_lshlrev_b32_e32 v69, 16, v52
	v_lshlrev_b32_e32 v68, 16, v48
	v_pk_mul_f32 v[20:21], v[64:65], v[64:65]
	v_lshlrev_b32_e32 v61, 16, v53
	v_lshlrev_b32_e32 v60, 16, v49
	v_pk_fma_f32 v[20:21], v[68:69], v[68:69], v[20:21]
	v_and_b32_e32 v59, 0xffff0000, v53
	v_and_b32_e32 v58, 0xffff0000, v49
	v_pk_fma_f32 v[20:21], v[60:61], v[60:61], v[20:21]
	v_lshlrev_b32_e32 v71, 16, v54
	v_lshlrev_b32_e32 v70, 16, v50
	v_pk_fma_f32 v[20:21], v[58:59], v[58:59], v[20:21]
	v_and_b32_e32 v67, 0xffff0000, v54
	v_and_b32_e32 v66, 0xffff0000, v50
	v_pk_fma_f32 v[20:21], v[70:71], v[70:71], v[20:21]
	v_lshlrev_b32_e32 v63, 16, v55
	v_lshlrev_b32_e32 v62, 16, v51
	v_pk_fma_f32 v[20:21], v[66:67], v[66:67], v[20:21]
	v_and_b32_e32 v57, 0xffff0000, v55
	v_and_b32_e32 v56, 0xffff0000, v51
	v_pk_fma_f32 v[20:21], v[62:63], v[62:63], v[20:21]
	v_and_b32_e32 v45, 0xffff0000, v112
	v_pk_fma_f32 v[20:21], v[56:57], v[56:57], v[20:21]
	v_and_b32_e32 v44, 0xffff0000, v108
	v_add_f32_e32 v20, v22, v20
	v_add_f32_e32 v22, v20, v21
	v_lshlrev_b32_e32 v49, 16, v112
	v_lshlrev_b32_e32 v48, 16, v108
	v_pk_mul_f32 v[20:21], v[44:45], v[44:45]
	v_lshlrev_b32_e32 v31, 16, v113
	v_lshlrev_b32_e32 v30, 16, v109
	v_pk_fma_f32 v[20:21], v[48:49], v[48:49], v[20:21]
	v_and_b32_e32 v29, 0xffff0000, v113
	v_and_b32_e32 v28, 0xffff0000, v109
	v_pk_fma_f32 v[20:21], v[30:31], v[30:31], v[20:21]
	v_lshlrev_b32_e32 v55, 16, v114
	v_lshlrev_b32_e32 v54, 16, v110
	v_pk_fma_f32 v[20:21], v[28:29], v[28:29], v[20:21]
	v_and_b32_e32 v53, 0xffff0000, v114
	v_and_b32_e32 v52, 0xffff0000, v110
	v_pk_fma_f32 v[20:21], v[54:55], v[54:55], v[20:21]
	v_lshlrev_b32_e32 v51, 16, v115
	v_lshlrev_b32_e32 v50, 16, v111
	v_pk_fma_f32 v[20:21], v[52:53], v[52:53], v[20:21]
	v_and_b32_e32 v47, 0xffff0000, v115
	v_and_b32_e32 v46, 0xffff0000, v111
	v_pk_fma_f32 v[20:21], v[50:51], v[50:51], v[20:21]
	s_nop 0
	v_pk_fma_f32 v[20:21], v[46:47], v[46:47], v[20:21]
	s_nop 0
	v_add_f32_e32 v20, v22, v20
	v_add_f32_e32 v20, v20, v21
	v_mov_b32_e32 v21, v20
	s_nop 1
	v_permlane32_swap_b32_e32 v20, v21
	v_add_f32_e32 v20, v20, v21
	v_fmamk_f32 v20, v20, 0x3c000000, v1
	v_cmp_gt_f32_e32 vcc, s33, v20
	v_mul_f32_e32 v21, 0x4b800000, v20
	s_nop 0
	v_cndmask_b32_e32 v20, v20, v21, vcc
	v_rsq_f32_e32 v20, v20
	s_nop 0
	v_mul_f32_e32 v21, 0x45800000, v20
	v_cndmask_b32_e32 v20, v20, v21, vcc
	v_mul_f32_e32 v91, 0x3dd53b94, v20
	ds_read_b128 v[20:23], v248 offset:16
	ds_read_b128 v[24:27], v248
	s_waitcnt lgkmcnt(0)
	v_mul_f32_e32 v20, v20, v91
	v_mul_f32_e32 v24, v24, v91
	v_mul_f32_e32 v25, v25, v91
	v_mul_f32_e32 v21, v21, v91
	v_mul_f32_e32 v26, v26, v91
	v_mul_f32_e32 v22, v22, v91
	v_mul_f32_e32 v27, v27, v91
	v_mul_f32_e32 v23, v23, v91
	v_mul_f32_e32 v24, v24, v106
	v_mul_f32_e32 v20, v20, v107
	v_mul_f32_e32 v25, v25, v104
	v_mul_f32_e32 v21, v21, v105
	v_mul_f32_e32 v26, v26, v101
	v_mul_f32_e32 v22, v22, v103
	v_mul_f32_e32 v27, v27, v97
	v_mul_f32_e32 v23, v23, v99
	v_cvt_pk_bf16_f32 v114, v24, v25
	v_cvt_pk_bf16_f32 v115, v26, v27
	v_cvt_pk_bf16_f32 v116, v20, v21
	v_cvt_pk_bf16_f32 v117, v22, v23
	ds_read_b128 v[20:23], v248 offset:80
	ds_read_b128 v[24:27], v248 offset:64
	v_and_b32_e32 v101, 0xffff0000, v8
	v_mov_b32_e32 v103, v101
	v_lshlrev_b32_e32 v97, 16, v9
	v_and_b32_e32 v99, 0xffff0000, v9
	s_waitcnt lgkmcnt(0)
; __device__ __forceinline__ u32x4 pack8(const float* f) { u32x4 w; w.x = cvtpk(f[0], f[1]); w.y = cvtpk(f[2], f[3]); w.z = cvtpk(f[4], f[5]); w.w = cvtpk(f[6], f[7]); return w; }
; __device__ __forceinline__ bf16x8 pack8(const f32x4& a, const f32x4& b) { u32x4 w; w.x = cpk(a.x, a.y); w.y = cpk(a.z, a.w); w.z = cpk(b.x, b.y); w.w = cpk(b.z, b.w); return __builtin_bit_cast(bf16x8, w); }
; template <int VAR>
; __device__ __forceinline__ void attn_unit(const AUnit& u, LAS char* lds) {
;     ...
;         for (int d0 = 0; d0 < 8; ++d0) { float f[8]; unpack8(__builtin_bit_cast(u32x4, qr[d0]), f);
;             const f32x4 g0 = *(const f32x4*)(u.gqn + d0 * 16 + hi * 8), g1 = *(const f32x4*)(u.gqn + d0 * 16 + hi * 8 + 4);
; #pragma unroll
;             for (int e = 0; e < 4; ++e) { f[e] *= rn * g0[e]; f[4 + e] *= rn * g1[e]; }
;             qr[d0] = __builtin_bit_cast(bf16x8, pack8(f)); }
	v_mul_f32_e32 v20, v20, v91
	v_mul_f32_e32 v24, v24, v91
	v_mul_f32_e32 v25, v25, v91
	v_mul_f32_e32 v21, v21, v91
	v_mul_f32_e32 v26, v26, v91
	v_mul_f32_e32 v22, v22, v91
	v_mul_f32_e32 v27, v27, v91
	v_mul_f32_e32 v23, v23, v91
	v_mul_f32_e32 v24, v24, v100
	v_mul_f32_e32 v20, v20, v102
	v_mul_f32_e32 v25, v25, v96
	v_mul_f32_e32 v21, v21, v98
	v_mul_f32_e32 v26, v26, v94
	v_mul_f32_e32 v22, v22, v95
	v_mul_f32_e32 v27, v27, v92
	v_mul_f32_e32 v23, v23, v93
	v_cvt_pk_bf16_f32 v118, v24, v25
	v_cvt_pk_bf16_f32 v119, v26, v27
	v_cvt_pk_bf16_f32 v120, v20, v21
	v_cvt_pk_bf16_f32 v121, v22, v23
	ds_read_b128 v[20:23], v248 offset:144
	ds_read_b128 v[24:27], v248 offset:128
	v_and_b32_e32 v100, 0xffff0000, v4
	v_lshlrev_b32_e32 v96, 16, v5
	v_and_b32_e32 v98, 0xffff0000, v5
	v_lshlrev_b32_e32 v92, 16, v6
	v_and_b32_e32 v94, 0xffff0000, v6
	v_mov_b32_e32 v9, v92
	v_lshlrev_b32_e32 v93, 16, v10
	v_and_b32_e32 v95, 0xffff0000, v10
	s_waitcnt lgkmcnt(0)
	v_mul_f32_e32 v20, v91, v20
	v_mul_f32_e32 v24, v91, v24
	v_mul_f32_e32 v25, v91, v25
	v_mul_f32_e32 v21, v91, v21
	v_mul_f32_e32 v26, v91, v26
	v_mul_f32_e32 v22, v91, v22
	v_mul_f32_e32 v27, v91, v27
	v_mul_f32_e32 v23, v91, v23
	v_mul_f32_e32 v24, v24, v82
	v_mul_f32_e32 v20, v20, v86
	v_mul_f32_e32 v25, v25, v78
	v_mul_f32_e32 v21, v21, v84
	v_mul_f32_e32 v26, v26, v76
	v_mul_f32_e32 v22, v22, v80
	v_mul_f32_e32 v27, v27, v74
	v_mul_f32_e32 v23, v23, v72
	v_cvt_pk_bf16_f32 v122, v24, v25
	v_cvt_pk_bf16_f32 v123, v26, v27
	v_cvt_pk_bf16_f32 v124, v20, v21
	v_cvt_pk_bf16_f32 v125, v22, v23
	ds_read_b128 v[20:23], v248 offset:208
	ds_read_b128 v[24:27], v248 offset:192
	v_lshlrev_b32_e32 v80, 16, v12
	v_and_b32_e32 v12, 0xffff0000, v12
	v_and_b32_e32 v78, 0xffff0000, v13
	v_lshlrev_b32_e32 v72, 16, v14
	v_and_b32_e32 v14, 0xffff0000, v14
	v_lshlrev_b32_e32 v84, 16, v7
	v_mov_b32_e32 v10, v14
	v_and_b32_e32 v86, 0xffff0000, v7
	v_mov_b32_e32 v5, v84
	v_mov_b32_e32 v7, v86
	s_waitcnt lgkmcnt(0)
	v_mul_f32_e32 v20, v91, v20
	v_mul_f32_e32 v24, v91, v24
	v_mul_f32_e32 v25, v91, v25
	v_mul_f32_e32 v21, v91, v21
	v_mul_f32_e32 v26, v91, v26
	v_mul_f32_e32 v22, v91, v22
	v_mul_f32_e32 v27, v91, v27
	v_mul_f32_e32 v23, v91, v23
	v_mul_f32_e32 v24, v24, v83
	v_mul_f32_e32 v20, v20, v87
	v_mul_f32_e32 v25, v25, v79
	v_mul_f32_e32 v21, v21, v85
	v_mul_f32_e32 v26, v26, v77
	v_mul_f32_e32 v22, v22, v81
	v_mul_f32_e32 v27, v27, v75
	v_mul_f32_e32 v23, v23, v73
	v_cvt_pk_bf16_f32 v126, v24, v25
	v_cvt_pk_bf16_f32 v127, v26, v27
	v_cvt_pk_bf16_f32 v128, v20, v21
	v_cvt_pk_bf16_f32 v129, v22, v23
	ds_read_b128 v[20:23], v248 offset:272
	ds_read_b128 v[24:27], v248 offset:256
	v_lshlrev_b32_e32 v73, 16, v18
	v_lshlrev_b32_e32 v81, 16, v16
	v_and_b32_e32 v79, 0xffff0000, v17
	v_lshlrev_b32_e32 v85, 16, v11
	v_and_b32_e32 v87, 0xffff0000, v11
	v_mov_b32_e32 v11, v94
	s_waitcnt lgkmcnt(0)
	v_mul_f32_e32 v20, v91, v20
	v_mul_f32_e32 v24, v91, v24
	v_mul_f32_e32 v25, v91, v25
	v_mul_f32_e32 v21, v91, v21
	v_mul_f32_e32 v26, v91, v26
	v_mul_f32_e32 v22, v91, v22
	v_mul_f32_e32 v27, v91, v27
	v_mul_f32_e32 v23, v91, v23
	v_mul_f32_e32 v24, v24, v68
	v_mul_f32_e32 v20, v20, v70
	v_mul_f32_e32 v25, v25, v64
	v_mul_f32_e32 v21, v21, v66
	v_mul_f32_e32 v26, v26, v60
	v_mul_f32_e32 v22, v22, v62
	v_mul_f32_e32 v27, v27, v58
	v_mul_f32_e32 v23, v23, v56
	v_cvt_pk_bf16_f32 v130, v24, v25
	v_cvt_pk_bf16_f32 v131, v26, v27
	v_cvt_pk_bf16_f32 v132, v20, v21
	v_cvt_pk_bf16_f32 v133, v22, v23
	ds_read_b128 v[20:23], v248 offset:336
	ds_read_b128 v[24:27], v248 offset:320
	v_lshl_or_b32 v64, v182, 3, v43
	v_lshlrev_b32_e32 v66, 16, v15
	v_and_b32_e32 v70, 0xffff0000, v15
	v_and_b32_e32 v15, 0xffff0000, v18
	v_lshlrev_b32_e32 v18, 16, v13
	v_and_b32_e32 v13, 0xffff0000, v16
	v_or_b32_e32 v16, 16, v64
	v_mov_b32_e32 v102, v13
	v_pk_mul_f32 v[102:103], v[102:103], v[102:103]
	v_mov_b32_e32 v6, v70
	s_waitcnt lgkmcnt(0)
	v_mul_f32_e32 v20, v91, v20
	v_mul_f32_e32 v24, v91, v24
	v_mul_f32_e32 v25, v91, v25
	v_mul_f32_e32 v21, v91, v21
	v_mul_f32_e32 v26, v91, v26
	v_mul_f32_e32 v22, v91, v22
	v_mul_f32_e32 v27, v91, v27
	v_mul_f32_e32 v23, v91, v23
	v_mul_f32_e32 v24, v24, v69
	v_mul_f32_e32 v20, v20, v71
	v_mul_f32_e32 v25, v25, v65
	v_mul_f32_e32 v21, v21, v67
	v_mul_f32_e32 v26, v26, v61
	v_mul_f32_e32 v22, v22, v63
	v_mul_f32_e32 v27, v27, v59
	v_mul_f32_e32 v23, v23, v57
	v_cvt_pk_bf16_f32 v134, v24, v25
	v_cvt_pk_bf16_f32 v135, v26, v27
	v_cvt_pk_bf16_f32 v136, v20, v21
	v_cvt_pk_bf16_f32 v137, v22, v23
	ds_read_b128 v[20:23], v248 offset:400
	ds_read_b128 v[24:27], v248 offset:384
	v_ashrrev_i32_e32 v65, 31, v64
	v_lshl_add_u64 v[60:61], v[64:65], 3, s[6:7]
	v_lshlrev_b32_e32 v67, 16, v19
	v_and_b32_e32 v71, 0xffff0000, v19
	v_lshlrev_b32_e32 v19, 16, v17
	v_ashrrev_i32_e32 v17, 31, v16
	v_lshl_add_u64 v[64:65], v[16:17], 3, s[6:7]
	v_mov_b32_e32 v16, v18
	v_mov_b32_e32 v17, v96
	s_waitcnt lgkmcnt(0)
	v_mul_f32_e32 v20, v91, v20
	v_mul_f32_e32 v24, v91, v24
	v_mul_f32_e32 v25, v91, v25
	v_mul_f32_e32 v21, v91, v21
	v_mul_f32_e32 v26, v91, v26
	v_mul_f32_e32 v22, v91, v22
	v_mul_f32_e32 v27, v91, v27
	v_mul_f32_e32 v23, v91, v23
	v_mul_f32_e32 v24, v24, v48
	v_mul_f32_e32 v20, v20, v54
	v_mul_f32_e32 v25, v25, v44
	v_mul_f32_e32 v21, v21, v52
	v_mul_f32_e32 v26, v26, v30
	v_mul_f32_e32 v22, v22, v50
	v_mul_f32_e32 v27, v27, v28
	v_mul_f32_e32 v23, v23, v46
	v_cvt_pk_bf16_f32 v138, v24, v25
	v_cvt_pk_bf16_f32 v139, v26, v27
	v_cvt_pk_bf16_f32 v140, v20, v21
	v_cvt_pk_bf16_f32 v141, v22, v23
	ds_read_b128 v[20:23], v248 offset:464
	ds_read_b128 v[24:27], v248 offset:448
	s_waitcnt lgkmcnt(0)
; __device__ __forceinline__ u32x4 pack8(const float* f) { u32x4 w; w.x = cvtpk(f[0], f[1]); w.y = cvtpk(f[2], f[3]); w.z = cvtpk(f[4], f[5]); w.w = cvtpk(f[6], f[7]); return w; }
; __device__ __forceinline__ bf16x8 pack8(const f32x4& a, const f32x4& b) { u32x4 w; w.x = cpk(a.x, a.y); w.y = cpk(a.z, a.w); w.z = cpk(b.x, b.y); w.w = cpk(b.z, b.w); return __builtin_bit_cast(bf16x8, w); }
; template <int VAR>
; __device__ __forceinline__ void attn_unit(const AUnit& u, LAS char* lds) {
;     ...
;         { auto rr = __builtin_amdgcn_permlane32_swap(__float_as_uint(ssr), __float_as_uint(ssr), false, false); ssr = __uint_as_float(rr[0]) + __uint_as_float(rr[1]); }
;         const float rn = rsqrtf(ssn * (1.f / 128) + NORM_EPS) * QSCALE, rr_ = rsqrtf(ssr * (1.f / ROPE) + NORM_EPS);
;     ...
;         const int pos = u.pos0 + wq * 32 + r32;
; #pragma unroll
;         for (int a = 0; a < 2; ++a) { float x1[8], x2[8]; unpack8(__builtin_bit_cast(u32x4, qr[8 + a]), x1); unpack8(__builtin_bit_cast(u32x4, qr[10 + a]), x2);
;             const int i0 = a * 16 + hi * 8;
;             const f32x4 ga0 = *(const f32x4*)(u.gqr + i0), ga1 = *(const f32x4*)(u.gqr + i0 + 4), gb0 = *(const f32x4*)(u.gqr + 32 + i0), gb1 = *(const f32x4*)(u.gqr + 32 + i0 + 4);
;             float y1[8], y2[8];
; #pragma unroll
;             for (int e = 0; e < 8; ++e) { const float v1 = x1[e] * rr_ * (e < 4 ? ga0[e & 3] : ga1[e & 3]), v2 = x2[e] * rr_ * (e < 4 ? gb0[e & 3] : gb1[e & 3]);
;                 const float2 cs = u.tab[pos * 32 + i0 + e];
;                 y1[e] = (v1 * cs.x - v2 * cs.y) * QSCALE; y2[e] = (v2 * cs.x + v1 * cs.y) * QSCALE; }
;             qr[8 + a] = __builtin_bit_cast(bf16x8, pack8(y1)); qr[10 + a] = __builtin_bit_cast(bf16x8, pack8(y2)); }
	v_mul_f32_e32 v20, v91, v20
	v_mul_f32_e32 v24, v91, v24
	v_mul_f32_e32 v25, v91, v25
	v_mul_f32_e32 v21, v91, v21
	v_mul_f32_e32 v26, v91, v26
	v_mul_f32_e32 v22, v91, v22
	v_mul_f32_e32 v27, v91, v27
	v_mul_f32_e32 v23, v91, v23
	v_mul_f32_e32 v24, v24, v49
	v_mul_f32_e32 v20, v20, v55
	v_mul_f32_e32 v25, v25, v45
	v_mul_f32_e32 v21, v21, v53
	v_mul_f32_e32 v26, v26, v31
	v_mul_f32_e32 v22, v22, v51
	v_mul_f32_e32 v27, v27, v29
	v_mul_f32_e32 v23, v23, v47
	v_cvt_pk_bf16_f32 v142, v24, v25
	v_cvt_pk_bf16_f32 v143, v26, v27
	v_cvt_pk_bf16_f32 v144, v20, v21
	v_cvt_pk_bf16_f32 v145, v22, v23
	ds_read_b128 v[20:23], v248 offset:512
	ds_read_b128 v[24:27], v248 offset:528
	ds_read_b128 v[28:31], v248 offset:640
	ds_read_b128 v[44:47], v248 offset:656
	global_load_dwordx4 v[48:51], v[60:61], off offset:48
	global_load_dwordx4 v[52:55], v[60:61], off offset:32
	global_load_dwordx4 v[56:59], v[60:61], off offset:16
	s_nop 0
	global_load_dwordx4 v[60:63], v[60:61], off
	s_waitcnt vmcnt(0)
	s_waitcnt lgkmcnt(0)
	v_mov_b32_e32 v82, v20
	v_mov_b32_e32 v68, v26
	v_lshlrev_b32_e32 v20, 16, v4
	v_mov_b32_e32 v69, v46
	v_mov_b32_e32 v46, v27
	v_mov_b32_e32 v26, v12
	v_mov_b32_e32 v27, v100
	v_mov_b32_e32 v74, v24
	v_mov_b32_e32 v75, v44
	v_mov_b32_e32 v44, v25
	v_mov_b32_e32 v24, v80
	v_mov_b32_e32 v25, v20
	v_pk_mul_f32 v[26:27], v[26:27], v[26:27]
	v_mov_b32_e32 v83, v28
	v_mov_b32_e32 v28, v21
	v_lshlrev_b32_e32 v21, 16, v8
	v_pk_fma_f32 v[24:25], v[24:25], v[24:25], v[26:27]
	v_mov_b32_e32 v76, v22
	v_mov_b32_e32 v77, v30
	v_mov_b32_e32 v30, v23
	v_mov_b32_e32 v22, v78
	v_mov_b32_e32 v23, v98
	v_pk_fma_f32 v[16:17], v[16:17], v[16:17], v[24:25]
	v_mov_b32_e32 v26, v81
	v_mov_b32_e32 v27, v21
	v_mov_b32_e32 v8, v72
	v_pk_fma_f32 v[16:17], v[22:23], v[22:23], v[16:17]
	v_mov_b32_e32 v22, v19
	v_mov_b32_e32 v23, v97
	v_pk_fma_f32 v[26:27], v[26:27], v[26:27], v[102:103]
	v_pk_fma_f32 v[8:9], v[8:9], v[8:9], v[16:17]
	v_mov_b32_e32 v24, v79
	v_mov_b32_e32 v25, v99
	v_pk_fma_f32 v[22:23], v[22:23], v[22:23], v[26:27]
	v_mov_b32_e32 v4, v66
	v_pk_fma_f32 v[8:9], v[10:11], v[10:11], v[8:9]
	v_mov_b32_e32 v10, v73
	v_mov_b32_e32 v11, v93
	v_pk_fma_f32 v[22:23], v[24:25], v[24:25], v[22:23]
	v_pk_fma_f32 v[4:5], v[4:5], v[4:5], v[8:9]
	v_mov_b32_e32 v16, v15
	v_mov_b32_e32 v17, v95
	v_pk_fma_f32 v[10:11], v[10:11], v[10:11], v[22:23]
	v_pk_fma_f32 v[4:5], v[6:7], v[6:7], v[4:5]
	v_mov_b32_e32 v6, v67
	v_mov_b32_e32 v7, v85
	v_pk_fma_f32 v[10:11], v[16:17], v[16:17], v[10:11]
	v_mov_b32_e32 v8, v71
	v_mov_b32_e32 v9, v87
	v_pk_fma_f32 v[6:7], v[6:7], v[6:7], v[10:11]
	v_pk_add_f32 v[4:5], v[4:5], v[4:5] op_sel:[0,1] op_sel_hi:[1,0]
	v_pk_fma_f32 v[6:7], v[8:9], v[8:9], v[6:7]
	s_nop 0
	v_pk_add_f32 v[4:5], v[4:5], v[6:7]
	s_nop 0
	v_pk_add_f32 v[4:5], v[4:5], v[6:7] op_sel:[0,1] op_sel_hi:[1,0]
	s_nop 0
	v_mov_b32_e32 v5, v4
	s_nop 1
	v_permlane32_swap_b32_e32 v4, v5
	v_add_f32_e32 v4, v4, v5
	v_fmamk_f32 v4, v4, 0x3c800000, v1
	v_cmp_gt_f32_e32 vcc, s33, v4
	v_mul_f32_e32 v5, 0x4b800000, v4
	s_nop 0
	v_cndmask_b32_e32 v4, v4, v5, vcc
	v_rsq_f32_e32 v4, v4
	s_nop 0
	v_mul_f32_e32 v5, 0x45800000, v4
	v_cndmask_b32_e32 v102, v4, v5, vcc
	v_pk_mul_f32 v[4:5], v[102:103], v[80:81] op_sel_hi:[0,1]
	v_pk_mul_f32 v[4:5], v[4:5], v[82:83]
	v_pk_mul_f32 v[20:21], v[102:103], v[20:21] op_sel_hi:[0,1]
	v_pk_mul_f32 v[6:7], v[4:5], v[60:61]
	v_pk_mul_f32 v[4:5], v[4:5], v[60:61] op_sel:[1,0] op_sel_hi:[0,1]
	v_add_f32_e32 v4, v4, v5
	v_mul_f32_e32 v9, 0x3dd53b94, v4
	v_pk_mul_f32 v[4:5], v[102:103], v[12:13] op_sel_hi:[0,1]
	v_sub_f32_e32 v6, v6, v7
	v_pk_mul_f32 v[4:5], v[4:5], v[28:29]
	v_mul_f32_e32 v8, 0x3dd53b94, v6
	v_pk_mul_f32 v[6:7], v[4:5], v[62:63]
	v_pk_mul_f32 v[4:5], v[4:5], v[62:63] op_sel:[1,0] op_sel_hi:[0,1]
	v_add_f32_e32 v4, v4, v5
	v_mul_f32_e32 v11, 0x3dd53b94, v4
	v_pk_mul_f32 v[4:5], v[102:103], v[18:19] op_sel_hi:[0,1]
	v_sub_f32_e32 v6, v6, v7
	v_pk_mul_f32 v[4:5], v[4:5], v[76:77]
	v_mul_f32_e32 v10, 0x3dd53b94, v6
	v_pk_mul_f32 v[6:7], v[4:5], v[56:57]
	v_pk_mul_f32 v[4:5], v[4:5], v[56:57] op_sel:[1,0] op_sel_hi:[0,1]
	v_add_f32_e32 v4, v4, v5
	v_mul_f32_e32 v13, 0x3dd53b94, v4
	v_pk_mul_f32 v[4:5], v[102:103], v[78:79] op_sel_hi:[0,1]
	v_sub_f32_e32 v6, v6, v7
	v_pk_mul_f32 v[4:5], v[4:5], v[30:31]
	v_mul_f32_e32 v12, 0x3dd53b94, v6
	v_pk_mul_f32 v[6:7], v[4:5], v[58:59]
	v_pk_mul_f32 v[4:5], v[4:5], v[58:59] op_sel:[1,0] op_sel_hi:[0,1]
	v_add_f32_e32 v4, v4, v5
	v_mul_f32_e32 v17, 0x3dd53b94, v4
	v_pk_mul_f32 v[4:5], v[102:103], v[72:73] op_sel_hi:[0,1]
	v_sub_f32_e32 v6, v6, v7
	v_pk_mul_f32 v[4:5], v[4:5], v[74:75]
	v_mul_f32_e32 v16, 0x3dd53b94, v6
	v_pk_mul_f32 v[6:7], v[4:5], v[52:53]
	v_pk_mul_f32 v[4:5], v[4:5], v[52:53] op_sel:[1,0] op_sel_hi:[0,1]
	v_add_f32_e32 v4, v4, v5
	v_mul_f32_e32 v19, 0x3dd53b94, v4
	v_pk_mul_f32 v[4:5], v[102:103], v[14:15] op_sel_hi:[0,1]
	v_sub_f32_e32 v6, v6, v7
	v_pk_mul_f32 v[4:5], v[4:5], v[44:45]
	v_mul_f32_e32 v18, 0x3dd53b94, v6
	v_pk_mul_f32 v[6:7], v[4:5], v[54:55]
	v_pk_mul_f32 v[4:5], v[4:5], v[54:55] op_sel:[1,0] op_sel_hi:[0,1]
	v_add_f32_e32 v4, v4, v5
	v_mul_f32_e32 v15, 0x3dd53b94, v4
	v_pk_mul_f32 v[4:5], v[102:103], v[66:67] op_sel_hi:[0,1]
	v_sub_f32_e32 v6, v6, v7
	v_pk_mul_f32 v[4:5], v[4:5], v[68:69]
	v_mul_f32_e32 v14, 0x3dd53b94, v6
	v_pk_mul_f32 v[6:7], v[4:5], v[48:49]
	v_pk_mul_f32 v[4:5], v[4:5], v[48:49] op_sel:[1,0] op_sel_hi:[0,1]
	v_add_f32_e32 v4, v4, v5
	v_mul_f32_e32 v23, 0x3dd53b94, v4
	v_pk_mul_f32 v[4:5], v[102:103], v[70:71] op_sel_hi:[0,1]
	v_sub_f32_e32 v6, v6, v7
	v_pk_mul_f32 v[4:5], v[4:5], v[46:47]
	v_mul_f32_e32 v22, 0x3dd53b94, v6
	v_pk_mul_f32 v[6:7], v[4:5], v[50:51]
	v_pk_mul_f32 v[4:5], v[4:5], v[50:51] op_sel:[1,0] op_sel_hi:[0,1]
	v_sub_f32_e32 v6, v6, v7
	v_add_f32_e32 v4, v4, v5
	v_mul_f32_e32 v6, 0x3dd53b94, v6
	v_mul_f32_e32 v4, 0x3dd53b94, v4
	v_cvt_pk_bf16_f32 v146, v8, v10
	v_cvt_pk_bf16_f32 v147, v12, v16
	v_cvt_pk_bf16_f32 v148, v18, v14
	v_cvt_pk_bf16_f32 v149, v22, v6
	v_cvt_pk_bf16_f32 v150, v9, v11
	v_cvt_pk_bf16_f32 v151, v13, v17
	v_cvt_pk_bf16_f32 v152, v19, v15
	v_cvt_pk_bf16_f32 v153, v23, v4
	ds_read_b128 v[4:7], v248 offset:592
	ds_read_b128 v[8:11], v248 offset:576
	ds_read_b128 v[12:15], v248 offset:720
	ds_read_b128 v[16:19], v248 offset:704
	s_waitcnt lgkmcnt(0)
; #define LAS __attribute__((address_space(3)))
; __device__ __forceinline__ u32x4 pack8(const float* f) { u32x4 w; w.x = cvtpk(f[0], f[1]); w.y = cvtpk(f[2], f[3]); w.z = cvtpk(f[4], f[5]); w.w = cvtpk(f[6], f[7]); return w; }
; __device__ __forceinline__ int v_rd_base(int lane) { return ((lane & 3) << 3) | (((lane >> 2) & 3) << 6) | (((lane >> 4) & 1) << 5) | (((lane >> 5) & 1) << 8); }
; #define AWAITV() asm volatile("s_waitcnt vmcnt(0)" ::: "memory")
; __device__ __forceinline__ bf16x8 pack8(const f32x4& a, const f32x4& b) { u32x4 w; w.x = cpk(a.x, a.y); w.y = cpk(a.z, a.w); w.z = cpk(b.x, b.y); w.w = cpk(b.z, b.w); return __builtin_bit_cast(bf16x8, w); }
; template <int VAR>
; __device__ __forceinline__ void attn_unit(const AUnit& u, LAS char* lds) {
;     ...
;         const int pos = u.pos0 + wq * 32 + r32;
; #pragma unroll
;         for (int a = 0; a < 2; ++a) { float x1[8], x2[8]; unpack8(__builtin_bit_cast(u32x4, qr[8 + a]), x1); unpack8(__builtin_bit_cast(u32x4, qr[10 + a]), x2);
;             const int i0 = a * 16 + hi * 8;
;             const f32x4 ga0 = *(const f32x4*)(u.gqr + i0), ga1 = *(const f32x4*)(u.gqr + i0 + 4), gb0 = *(const f32x4*)(u.gqr + 32 + i0), gb1 = *(const f32x4*)(u.gqr + 32 + i0 + 4);
;             float y1[8], y2[8];
; #pragma unroll
;             for (int e = 0; e < 8; ++e) { const float v1 = x1[e] * rr_ * (e < 4 ? ga0[e & 3] : ga1[e & 3]), v2 = x2[e] * rr_ * (e < 4 ? gb0[e & 3] : gb1[e & 3]);
;                 const float2 cs = u.tab[pos * 32 + i0 + e];
;                 y1[e] = (v1 * cs.x - v2 * cs.y) * QSCALE; y2[e] = (v2 * cs.x + v1 * cs.y) * QSCALE; }
;             qr[8 + a] = __builtin_bit_cast(bf16x8, pack8(y1)); qr[10 + a] = __builtin_bit_cast(bf16x8, pack8(y2)); }
;     }
;     float m_reg = -1e30f, l_reg = 0.f; f32x16 o[4]; o[0] = f32x16{}; o[1] = f32x16{}; o[2] = f32x16{}; o[3] = f32x16{};
;     LAS float* wsf = (LAS float*)(lds + OFF_WS) + wid * 64; LAS float* li_l = wsf; LAS float* al_l = wsf + 32;
;     const int vb0 = (int)(unsigned)(uintptr_t)lds + v_rd_base(lane);
;     AWAITV();
;     __syncthreads();
	v_mov_b32_e32 v22, v8
	v_mov_b32_e32 v23, v16
	v_pk_mul_f32 v[48:49], v[20:21], v[22:23]
	global_load_dwordx4 v[20:23], v[64:65], off offset:48
	global_load_dwordx4 v[24:27], v[64:65], off offset:32
	global_load_dwordx4 v[28:31], v[64:65], off offset:16
	global_load_dwordx4 v[44:47], v[64:65], off
	v_mov_b32_e32 v16, v9
	s_waitcnt vmcnt(0)
	v_pk_mul_f32 v[50:51], v[48:49], v[44:45]
	s_nop 0
	v_sub_f32_e32 v8, v50, v51
	v_pk_mul_f32 v[44:45], v[48:49], v[44:45] op_sel:[1,0] op_sel_hi:[0,1]
	v_mul_f32_e32 v43, 0x3dd53b94, v8
	v_add_f32_e32 v8, v44, v45
	v_pk_mul_f32 v[44:45], v[102:103], v[100:101] op_sel_hi:[0,1]
	v_mul_f32_e32 v48, 0x3dd53b94, v8
	v_pk_mul_f32 v[8:9], v[44:45], v[16:17]
	s_nop 0
	v_pk_mul_f32 v[16:17], v[8:9], v[46:47]
	v_pk_mul_f32 v[8:9], v[8:9], v[46:47] op_sel:[1,0] op_sel_hi:[0,1]
	v_sub_f32_e32 v16, v16, v17
	v_add_f32_e32 v8, v8, v9
	v_mul_f32_e32 v44, 0x3dd53b94, v16
	v_mul_f32_e32 v45, 0x3dd53b94, v8
	v_pk_mul_f32 v[8:9], v[102:103], v[96:97] op_sel_hi:[0,1]
	v_mov_b32_e32 v16, v10
	v_mov_b32_e32 v17, v18
	v_pk_mul_f32 v[8:9], v[8:9], v[16:17]
	v_mov_b32_e32 v18, v11
	v_pk_mul_f32 v[16:17], v[8:9], v[28:29]
	v_pk_mul_f32 v[8:9], v[8:9], v[28:29] op_sel:[1,0] op_sel_hi:[0,1]
	v_add_f32_e32 v8, v8, v9
	v_sub_f32_e32 v10, v16, v17
	v_mul_f32_e32 v17, 0x3dd53b94, v8
	v_pk_mul_f32 v[8:9], v[102:103], v[98:99] op_sel_hi:[0,1]
	v_pk_mul_f32 v[8:9], v[8:9], v[18:19]
	v_mul_f32_e32 v16, 0x3dd53b94, v10
	v_pk_mul_f32 v[10:11], v[8:9], v[30:31]
	v_pk_mul_f32 v[8:9], v[8:9], v[30:31] op_sel:[1,0] op_sel_hi:[0,1]
	v_sub_f32_e32 v10, v10, v11
	v_add_f32_e32 v8, v8, v9
	v_mul_f32_e32 v18, 0x3dd53b94, v10
	v_mul_f32_e32 v19, 0x3dd53b94, v8
	v_pk_mul_f32 v[8:9], v[102:103], v[92:93] op_sel_hi:[0,1]
	v_mov_b32_e32 v10, v4
	v_mov_b32_e32 v11, v12
	v_pk_mul_f32 v[8:9], v[8:9], v[10:11]
	v_mov_b32_e32 v12, v5
	v_pk_mul_f32 v[10:11], v[8:9], v[24:25]
	v_pk_mul_f32 v[8:9], v[8:9], v[24:25] op_sel:[1,0] op_sel_hi:[0,1]
	v_sub_f32_e32 v4, v10, v11
	v_mul_f32_e32 v10, 0x3dd53b94, v4
	v_add_f32_e32 v4, v8, v9
	v_pk_mul_f32 v[8:9], v[102:103], v[94:95] op_sel_hi:[0,1]
	v_mul_f32_e32 v11, 0x3dd53b94, v4
	v_pk_mul_f32 v[4:5], v[8:9], v[12:13]
	v_cvt_pk_bf16_f32 v154, v43, v44
	v_cvt_pk_bf16_f32 v155, v16, v18
	v_mov_b32_e32 v16, v3
	v_pk_mul_f32 v[8:9], v[4:5], v[26:27]
	v_pk_mul_f32 v[4:5], v[4:5], v[26:27] op_sel:[1,0] op_sel_hi:[0,1]
	v_sub_f32_e32 v8, v8, v9
	v_add_f32_e32 v4, v4, v5
	v_mul_f32_e32 v12, 0x3dd53b94, v8
	v_mul_f32_e32 v13, 0x3dd53b94, v4
	v_pk_mul_f32 v[4:5], v[102:103], v[84:85] op_sel_hi:[0,1]
	v_mov_b32_e32 v8, v6
	v_mov_b32_e32 v9, v14
	v_pk_mul_f32 v[4:5], v[4:5], v[8:9]
	v_mov_b32_e32 v14, v7
	v_pk_mul_f32 v[8:9], v[4:5], v[20:21]
	v_pk_mul_f32 v[4:5], v[4:5], v[20:21] op_sel:[1,0] op_sel_hi:[0,1]
	v_add_f32_e32 v4, v4, v5
	v_sub_f32_e32 v6, v8, v9
	v_mul_f32_e32 v9, 0x3dd53b94, v4
	v_pk_mul_f32 v[4:5], v[102:103], v[86:87] op_sel_hi:[0,1]
	v_pk_mul_f32 v[4:5], v[4:5], v[14:15]
	v_mul_f32_e32 v8, 0x3dd53b94, v6
	v_pk_mul_f32 v[6:7], v[4:5], v[22:23]
	v_pk_mul_f32 v[4:5], v[4:5], v[22:23] op_sel:[1,0] op_sel_hi:[0,1]
	v_sub_f32_e32 v6, v6, v7
	v_add_f32_e32 v4, v4, v5
	v_mul_f32_e32 v6, 0x3dd53b94, v6
	v_mul_f32_e32 v4, 0x3dd53b94, v4
	v_lshlrev_b32_e32 v5, 4, v181
	v_cvt_pk_bf16_f32 v156, v10, v12
	v_cvt_pk_bf16_f32 v157, v8, v6
	v_cvt_pk_bf16_f32 v158, v48, v45
	v_cvt_pk_bf16_f32 v159, v17, v19
	v_cvt_pk_bf16_f32 v160, v11, v13
	v_cvt_pk_bf16_f32 v161, v9, v4
	v_lshlrev_b32_e32 v4, 3, v88
	v_and_b32_e32 v6, 0xc0, v5
	v_lshlrev_b32_e32 v7, 1, v181
	v_and_or_b32 v6, v4, 24, v6
	v_and_b32_e32 v7, 32, v7
	v_and_b32_e32 v4, 0x100, v4
	v_or3_b32 v4, v6, v7, v4
	v_add_u32_e32 v163, 0, v4
	v_and_b32_e32 v4, 0xf0, v5
	v_bitop3_b32 v185, v162, v4, 32 bitop3:0x36
	v_bitop3_b32 v186, v162, v4, 64 bitop3:0x36
	v_bitop3_b32 v187, v162, v4, s24 bitop3:0x36
	v_bitop3_b32 v207, v162, v4, s23 bitop3:0x36
	v_bitop3_b32 v208, v162, v4, s25 bitop3:0x36
	v_bitop3_b32 v209, v162, v4, s14 bitop3:0x36
	v_bitop3_b32 v210, v162, v4, s15 bitop3:0x36
	v_lshlrev_b32_e32 v4, 7, v180
	v_sub_u32_e32 v211, v183, v4
	v_add_u32_e32 v224, s10, v4
	v_bitop3_b32 v4, v32, 15, v181 bitop3:0x48
	v_lshl_or_b32 v34, v4, 4, v34
	v_bitop3_b32 v4, v33, 7, v181 bitop3:0x48
	s_waitcnt vmcnt(0)
	v_bitop3_b32 v184, v162, v5, s20 bitop3:0x78
	v_and_b32_e32 v5, 0x70, v89
	v_lshl_or_b32 v38, v4, 4, v38
	v_mov_b32_e32 v17, v3
	v_bitop3_b32 v213, v162, v5, 32 bitop3:0x36
	v_bitop3_b32 v214, v162, v5, 64 bitop3:0x36
	v_bitop3_b32 v215, v162, v5, s24 bitop3:0x36
	v_lshl_add_u64 v[174:175], s[50:51], 0, v[34:35]
	v_lshl_add_u64 v[176:177], s[52:53], 0, v[38:39]
	v_mov_b32_e32 v4, v3
	v_mov_b32_e32 v5, v3
	v_mov_b32_e32 v6, v3
	v_mov_b32_e32 v7, v3
	v_mov_b32_e32 v8, v3
	v_mov_b32_e32 v9, v3
	v_mov_b32_e32 v10, v3
	v_mov_b32_e32 v11, v3
	v_mov_b32_e32 v12, v3
	v_mov_b32_e32 v13, v3
	v_mov_b32_e32 v14, v3
	v_mov_b32_e32 v15, v3
	v_mov_b64_e32 v[32:33], v[16:17]
	v_mov_b64_e32 v[48:49], v[16:17]
	v_mov_b64_e32 v[64:65], v[16:17]
	v_mov_b64_e32 v[80:81], v[16:17]
	v_add3_u32 v216, v183, v184, s22
	v_add3_u32 v217, v183, v185, s22
	v_add3_u32 v218, v183, v186, s22
	v_add3_u32 v219, v183, v187, s22
	v_add3_u32 v220, v183, v207, s22
	v_add3_u32 v221, v183, v208, s22
	v_add3_u32 v222, v183, v209, s22
	v_add3_u32 v223, v183, v210, s22
	v_mov_b64_e32 v[30:31], v[14:15]
	v_mov_b64_e32 v[28:29], v[12:13]
	v_mov_b64_e32 v[26:27], v[10:11]
	v_mov_b64_e32 v[24:25], v[8:9]
	v_mov_b64_e32 v[22:23], v[6:7]
	v_mov_b64_e32 v[20:21], v[4:5]
	v_mov_b64_e32 v[18:19], v[2:3]
	v_mov_b64_e32 v[46:47], v[14:15]
	v_mov_b64_e32 v[44:45], v[12:13]
	v_mov_b64_e32 v[42:43], v[10:11]
	v_mov_b64_e32 v[40:41], v[8:9]
	v_mov_b64_e32 v[38:39], v[6:7]
	v_mov_b64_e32 v[36:37], v[4:5]
	v_mov_b64_e32 v[34:35], v[2:3]
	v_mov_b64_e32 v[62:63], v[14:15]
	v_mov_b64_e32 v[60:61], v[12:13]
	v_mov_b64_e32 v[58:59], v[10:11]
	v_mov_b64_e32 v[56:57], v[8:9]
	v_mov_b64_e32 v[54:55], v[6:7]
	v_mov_b64_e32 v[52:53], v[4:5]
	v_mov_b64_e32 v[50:51], v[2:3]
	v_mov_b64_e32 v[78:79], v[14:15]
	v_mov_b64_e32 v[76:77], v[12:13]
	v_mov_b64_e32 v[74:75], v[10:11]
	v_mov_b64_e32 v[72:73], v[8:9]
	v_mov_b64_e32 v[70:71], v[6:7]
	v_mov_b64_e32 v[68:69], v[4:5]
	v_mov_b64_e32 v[66:67], v[2:3]
	s_waitcnt lgkmcnt(0)
	s_barrier
	v_readfirstlane_b32 s93, v181
	s_nop 3
	s_lshr_b32 s93, s93, 8
	s_cmp_eq_u32 s93, 0
	s_cbranch_scc0 .Latt_startB
	s_setprio 1

; template <int VAR>
; __device__ __forceinline__ void attn_unit(const AUnit& u, LAS char* lds) {
;     ...
;     for (int j = 0; j < u.nt; j += 2) {
;         ASTEP(0, j);
;         if (j + 1 < u.nt) ASTEP(1, j + 1);
;     }
.Latt_h5pA_skip:
	s_waitcnt vmcnt(0)
	s_waitcnt lgkmcnt(0)
	s_barrier
	s_barrier
	s_setprio 0
	s_branch .Latt_exit
